# phase mixing in P3 by XCD parity: odd workgroup ids run attention before the FFT long conv
# speedup vs baseline: 1.0094x; 1.0057x over previous
.LBB0_678:
	s_or_b64 exec, exec, s[40:41]
	s_bitcmp1_b32 s93, 0
	s_cbranch_scc0 .Lp3_fft_entry
	v_mov_b32_e32 v199, 1
	s_branch .LBB0_722
